# v36 + FFN-up halo publish: each weight-row-scale quad loaded once per pair of rows (8 -> 4 serialized round trips), later code kept at its byte position with unreachable padding
# baseline (speedup 1.0000x reference)
.LBB0_1372:
	s_or_b64 exec, exec, s[4:5]
	s_lshl_b32 s4, s42, 7
	v_lshlrev_b32_e32 v204, 3, v239
	s_or_b32 s4, s4, s76
	v_cvt_f32_i32_e32 v195, v119
	v_cvt_f32_i32_e32 v194, v118
	v_cvt_f32_i32_e32 v193, v121
	v_cvt_f32_i32_e32 v192, v120
	v_cvt_f32_i32_e32 v191, v115
	v_cvt_f32_i32_e32 v190, v114
	v_cvt_f32_i32_e32 v189, v117
	v_cvt_f32_i32_e32 v188, v116
	v_add_u32_e32 v186, s4, v204
	s_lshl_b32 s42, s42, 8
	s_lshl_b32 s31, s40, 1
	v_ashrrev_i32_e32 v187, 31, v186
	v_or_b32_e32 v122, s41, v222
	s_ashr_i32 s43, s42, 31
	v_ashrrev_i32_e32 v205, 31, v204
	v_cmp_eq_u32_e64 s[4:5], 0, v122
	s_mul_hi_i32 s35, s31, 0x1c000
	s_mul_i32 s56, s31, 0x1c000
	v_lshlrev_b64 v[114:115], 2, v[186:187]
	s_and_saveexec_b64 s[18:19], s[4:5]
	s_cbranch_execz .LBB0_1374
	s_lshl_b64 vcc, s[42:43], 2
	s_add_u32 vcc_lo, s94, vcc_lo
	s_addc_u32 vcc_hi, s95, vcc_hi
	v_lshl_add_u64 v[124:125], v[204:205], 2, vcc
	global_load_dwordx4 v[244:247], v[124:125], off
	s_add_u32 vcc_lo, s69, s56
	v_pk_mul_f32 v[120:121], v[162:163], v[192:193] op_sel_hi:[0,1]
	v_pk_mul_f32 v[122:123], v[162:163], v[194:195] op_sel_hi:[0,1]
	s_addc_u32 vcc_hi, s70, s35
	s_or_b32 s57, s31, 1
	s_mul_hi_i32 s79, s57, 0x1c000
	s_mul_i32 s57, s57, 0x1c000
	s_waitcnt vmcnt(0)
	v_pk_mul_f32 v[116:117], v[122:123], v[244:245]
	v_pk_mul_f32 v[118:119], v[120:121], v[246:247]
	v_lshl_add_u64 v[120:121], vcc, 0, v[114:115]
	global_store_dwordx4 v[120:121], v[116:119], off
	s_add_u32 vcc_lo, s69, s57
	v_pk_mul_f32 v[120:121], v[162:163], v[188:189] op_sel:[1,0]
	v_pk_mul_f32 v[122:123], v[162:163], v[190:191] op_sel:[1,0]
	s_addc_u32 vcc_hi, s70, s79
	v_pk_mul_f32 v[116:117], v[122:123], v[244:245]
	v_pk_mul_f32 v[118:119], v[120:121], v[246:247]
	v_lshl_add_u64 v[120:121], vcc, 0, v[114:115]
	global_store_dwordx4 v[120:121], v[116:119], off

.LBB0_1376:
	s_or_b64 exec, exec, s[18:19]
	v_cvt_f32_i32_e32 v121, v103
	v_cvt_f32_i32_e32 v120, v102
	v_cvt_f32_i32_e32 v125, v105
	v_cvt_f32_i32_e32 v124, v104
	v_cvt_f32_i32_e32 v119, v99
	v_cvt_f32_i32_e32 v118, v98
	v_cvt_f32_i32_e32 v123, v101
	v_cvt_f32_i32_e32 v122, v100
	s_and_saveexec_b64 s[18:19], s[4:5]
	s_cbranch_execz .LBB0_1378
	s_lshl_b64 vcc, s[42:43], 2
	s_add_u32 vcc_lo, s94, vcc_lo
	s_addc_u32 vcc_hi, s95, vcc_hi
	v_lshl_add_u64 v[108:109], v[204:205], 2, vcc
	global_load_dwordx4 v[244:247], v[108:109], off offset:16
	s_add_u32 vcc_lo, s69, s56
	v_pk_mul_f32 v[102:103], v[162:163], v[124:125] op_sel_hi:[0,1]
	v_pk_mul_f32 v[104:105], v[162:163], v[120:121] op_sel_hi:[0,1]
	s_addc_u32 vcc_hi, s70, s35
	s_or_b32 s57, s31, 1
	s_mul_hi_i32 s79, s57, 0x1c000
	s_mul_i32 s57, s57, 0x1c000
	s_waitcnt vmcnt(0)
	v_pk_mul_f32 v[98:99], v[104:105], v[244:245]
	v_pk_mul_f32 v[100:101], v[102:103], v[246:247]
	v_lshl_add_u64 v[102:103], vcc, 0, v[114:115]
	global_store_dwordx4 v[102:103], v[98:101], off offset:16
	s_add_u32 vcc_lo, s69, s57
	v_pk_mul_f32 v[102:103], v[162:163], v[122:123] op_sel:[1,0]
	v_pk_mul_f32 v[104:105], v[162:163], v[118:119] op_sel:[1,0]
	s_addc_u32 vcc_hi, s70, s79
	v_pk_mul_f32 v[98:99], v[104:105], v[244:245]
	v_pk_mul_f32 v[100:101], v[102:103], v[246:247]
	v_lshl_add_u64 v[102:103], vcc, 0, v[114:115]
	global_store_dwordx4 v[102:103], v[98:101], off offset:16

.LBB0_1380:
	s_or_b64 exec, exec, s[18:19]
	v_cvt_f32_i32_e32 v221, v87
	v_cvt_f32_i32_e32 v220, v86
	v_cvt_f32_i32_e32 v219, v89
	v_cvt_f32_i32_e32 v218, v88
	v_cvt_f32_i32_e32 v217, v83
	v_cvt_f32_i32_e32 v216, v82
	v_cvt_f32_i32_e32 v215, v85
	v_cvt_f32_i32_e32 v214, v84
	s_and_saveexec_b64 s[18:19], s[4:5]
	s_cbranch_execz .LBB0_1382
	s_lshl_b64 vcc, s[42:43], 2
	s_add_u32 vcc_lo, s94, vcc_lo
	s_addc_u32 vcc_hi, s95, vcc_hi
	v_lshl_add_u64 v[90:91], v[204:205], 2, vcc
	global_load_dwordx4 v[244:247], v[90:91], off offset:512
	s_add_u32 vcc_lo, s69, s56
	v_pk_mul_f32 v[86:87], v[162:163], v[218:219] op_sel_hi:[0,1]
	s_addc_u32 vcc_hi, s70, s35
	v_pk_mul_f32 v[88:89], v[162:163], v[220:221] op_sel_hi:[0,1]
	s_or_b32 s57, s31, 1
	s_mul_hi_i32 s79, s57, 0x1c000
	s_mul_i32 s57, s57, 0x1c000
	s_waitcnt vmcnt(0)
	v_pk_mul_f32 v[84:85], v[86:87], v[246:247]
	v_lshl_add_u64 v[86:87], vcc, 0, v[114:115]
	v_add_co_u32_e32 v86, vcc, s1, v86
	v_pk_mul_f32 v[82:83], v[88:89], v[244:245]
	s_nop 0
	v_addc_co_u32_e32 v87, vcc, 0, v87, vcc
	global_store_dwordx4 v[86:87], v[82:85], off
	s_add_u32 vcc_lo, s69, s57
	v_pk_mul_f32 v[86:87], v[162:163], v[214:215] op_sel:[1,0]
	s_addc_u32 vcc_hi, s70, s79
	v_pk_mul_f32 v[88:89], v[162:163], v[216:217] op_sel:[1,0]
	v_pk_mul_f32 v[84:85], v[86:87], v[246:247]
	v_lshl_add_u64 v[86:87], vcc, 0, v[114:115]
	v_add_co_u32_e32 v86, vcc, 0xe000, v86
	v_pk_mul_f32 v[82:83], v[88:89], v[244:245]
	s_nop 0
	v_addc_co_u32_e32 v87, vcc, 0, v87, vcc
	global_store_dwordx4 v[86:87], v[82:85], off

.LBB0_1384:
	s_or_b64 exec, exec, s[18:19]
	v_cvt_f32_i32_e32 v181, v71
	v_cvt_f32_i32_e32 v180, v70
	v_cvt_f32_i32_e32 v185, v73
	v_cvt_f32_i32_e32 v184, v72
	v_cvt_f32_i32_e32 v179, v67
	v_cvt_f32_i32_e32 v178, v66
	v_cvt_f32_i32_e32 v183, v69
	v_cvt_f32_i32_e32 v182, v68
	s_and_saveexec_b64 s[18:19], s[4:5]
	s_cbranch_execz .LBB0_1386
	s_lshl_b64 s[4:5], s[42:43], 2
	s_add_u32 s4, s94, s4
	s_addc_u32 s5, s95, s5
	v_lshl_add_u64 v[74:75], v[204:205], 2, s[4:5]
	global_load_dwordx4 v[244:247], v[74:75], off offset:528
	s_add_u32 s4, s69, s56
	v_pk_mul_f32 v[70:71], v[162:163], v[184:185] op_sel_hi:[0,1]
	s_addc_u32 s5, s70, s35
	v_pk_mul_f32 v[72:73], v[162:163], v[180:181] op_sel_hi:[0,1]
	s_waitcnt vmcnt(0)
	v_pk_mul_f32 v[68:69], v[70:71], v[246:247]
	v_lshl_add_u64 v[70:71], s[4:5], 0, v[114:115]
	v_add_co_u32_e32 v70, vcc, s1, v70
	v_pk_mul_f32 v[66:67], v[72:73], v[244:245]
	s_nop 0
	v_addc_co_u32_e32 v71, vcc, 0, v71, vcc
	global_store_dwordx4 v[70:71], v[66:69], off offset:16
	s_or_b32 s4, s31, 1
	s_mul_hi_i32 s5, s4, 0x1c000
	s_mul_i32 s4, s4, 0x1c000
	s_add_u32 s4, s69, s4
	v_pk_mul_f32 v[70:71], v[162:163], v[182:183] op_sel:[1,0]
	s_addc_u32 s5, s70, s5
	v_pk_mul_f32 v[72:73], v[162:163], v[178:179] op_sel:[1,0]
	v_pk_mul_f32 v[68:69], v[70:71], v[246:247]
	v_lshl_add_u64 v[70:71], s[4:5], 0, v[114:115]
	v_add_co_u32_e32 v70, vcc, 0xe000, v70
	v_pk_mul_f32 v[66:67], v[72:73], v[244:245]
	s_nop 0
	v_addc_co_u32_e32 v71, vcc, 0, v71, vcc
	global_store_dwordx4 v[70:71], v[66:69], off offset:16
.LBB0_1386:
	s_or_b64 exec, exec, s[18:19]
	s_waitcnt lgkmcnt(0)
	v_fmamk_f32 v66, v130, 0x39800000, v237
	v_rsq_f32_e32 v66, v66
	v_fmamk_f32 v67, v131, 0x39800000, v237
	v_rsq_f32_e32 v67, v67
	v_fmamk_f32 v68, v132, 0x39800000, v237
	v_pk_mul_f32 v[130:131], v[134:135], v[66:67]
	v_cvt_f32_i32_e32 v135, v63
	v_cvt_f32_i32_e32 v134, v62
	v_cndmask_b32_e64 v66, 0, 1, s[12:13]
	v_rsq_f32_e32 v68, v68
	v_fmamk_f32 v69, v133, 0x39800000, v237
	v_cmp_ne_u32_e64 s[4:5], 1, v66
	v_rsq_f32_e32 v69, v69
	s_nop 0
	v_pk_mul_f32 v[132:133], v[136:137], v[68:69]
	v_cvt_f32_i32_e32 v137, v65
	v_cvt_f32_i32_e32 v136, v64
	s_and_saveexec_b64 s[18:19], s[6:7]
	s_cbranch_execz .LBB0_1403
	v_add_lshl_u32 v66, s47, v106, 4
	v_add_u32_e32 v68, 0, v66
	v_mov_b32_e32 v67, v132
	v_pk_mul_f32 v[64:65], v[132:133], v[136:137] op_sel_hi:[0,1]
	v_pk_mul_f32 v[62:63], v[132:133], v[134:135] op_sel_hi:[0,1]
	v_add_u32_e32 v68, 0x20c00, v68
	s_and_b64 vcc, exec, s[4:5]
	ds_write_b128 v68, v[62:65]
	s_cbranch_vccnz .LBB0_1389
	s_lshl_b64 s[6:7], s[42:43], 2
	s_add_u32 s6, s94, s6
	s_addc_u32 s7, s95, s7
	v_lshl_add_u64 v[68:69], v[204:205], 2, s[6:7]
	global_load_dwordx4 v[248:251], v[68:69], off
	s_add_u32 s6, s71, s56
	s_addc_u32 s7, s72, s35
	s_waitcnt vmcnt(0)
	v_pk_mul_f32 v[64:65], v[64:65], v[250:251]
	v_pk_mul_f32 v[62:63], v[62:63], v[248:249]
	v_lshl_add_u64 v[68:69], v[186:187], 2, s[6:7]
	global_store_dwordx4 v[68:69], v[62:65], off
.LBB0_1389:
	s_nop 1
	v_cvt_f32_i32_e32 v63, v59
	v_cvt_f32_i32_e32 v65, v61
	v_cvt_f32_i32_e32 v64, v60
	v_cvt_f32_i32_e32 v62, v58
	v_mov_b32_e32 v68, v133
	v_add_u32_e32 v66, s92, v66
	v_pk_mul_f32 v[64:65], v[68:69], v[64:65] op_sel_hi:[0,1]
	v_pk_mul_f32 v[62:63], v[68:69], v[62:63] op_sel_hi:[0,1]
	s_and_b64 vcc, exec, s[4:5]
	ds_write_b128 v66, v[62:65] offset:16
	s_cbranch_vccnz .LBB0_1391
	s_lshl_b64 s[6:7], s[42:43], 2
	s_add_u32 s6, s94, s6
	s_addc_u32 s7, s95, s7
	v_lshl_add_u64 v[68:69], v[204:205], 2, s[6:7]
	s_or_b32 s6, s31, 1
	s_mul_hi_i32 s7, s6, 0x1c000
	s_mul_i32 s6, s6, 0x1c000
	s_add_u32 s6, s71, s6
	s_addc_u32 s7, s72, s7
	v_pk_mul_f32 v[64:65], v[64:65], v[250:251]
	v_pk_mul_f32 v[62:63], v[62:63], v[248:249]
	v_lshl_add_u64 v[68:69], v[186:187], 2, s[6:7]
	global_store_dwordx4 v[68:69], v[62:65], off

.LBB0_1393:
	s_andn2_b64 vcc, exec, s[6:7]
	s_cbranch_vccnz .LBB0_1395
	s_lshl_b64 s[6:7], s[42:43], 2
	s_add_u32 s6, s94, s6
	s_addc_u32 s7, s95, s7
	v_lshl_add_u64 v[76:77], v[204:205], 2, s[6:7]
	global_load_dwordx4 v[248:251], v[76:77], off offset:16
	s_add_u32 s6, s71, s56
	s_addc_u32 s7, s72, s35
	s_waitcnt vmcnt(0)
	v_pk_mul_f32 v[64:65], v[64:65], v[250:251]
	v_pk_mul_f32 v[62:63], v[62:63], v[248:249]
	v_lshl_add_u64 v[72:73], s[6:7], 0, v[114:115]
	global_store_dwordx4 v[72:73], v[62:65], off offset:16
	v_mov_b32_e32 v72, v133
	v_mov_b32_e32 v73, v133
	v_cvt_f32_i32_e32 v63, v27
	v_cvt_f32_i32_e32 v62, v26
	v_cvt_f32_i32_e32 v65, v29
	v_cvt_f32_i32_e32 v64, v28
	s_or_b32 s6, s31, 1
	v_pk_mul_f32 v[62:63], v[68:69], v[62:63]
	s_mul_hi_i32 s7, s6, 0x1c000
	v_pk_mul_f32 v[64:65], v[72:73], v[64:65]
	ds_write_b128 v70, v[62:65] offset:16
	s_mul_i32 s6, s6, 0x1c000
	s_add_u32 s6, s71, s6
	s_addc_u32 s7, s72, s7
	v_pk_mul_f32 v[64:65], v[64:65], v[250:251]
	v_pk_mul_f32 v[62:63], v[62:63], v[248:249]
	v_lshl_add_u64 v[70:71], s[6:7], 0, v[114:115]
	global_store_dwordx4 v[70:71], v[62:65], off offset:16

.LBB0_1397:
	s_andn2_b64 vcc, exec, s[6:7]
	s_cbranch_vccnz .LBB0_1399
	s_lshl_b64 s[6:7], s[42:43], 2
	s_add_u32 s6, s94, s6
	s_addc_u32 s7, s95, s7
	v_lshl_add_u64 v[76:77], v[204:205], 2, s[6:7]
	global_load_dwordx4 v[248:251], v[76:77], off offset:512
	s_add_u32 s6, s71, s56
	s_addc_u32 s7, s72, s35
	s_waitcnt vmcnt(0)
	v_pk_mul_f32 v[62:63], v[62:63], v[248:249]
	v_lshl_add_u64 v[72:73], s[6:7], 0, v[114:115]
	v_add_co_u32_e32 v72, vcc, s1, v72
	v_pk_mul_f32 v[64:65], v[64:65], v[250:251]
	s_nop 0
	v_addc_co_u32_e32 v73, vcc, 0, v73, vcc
	global_store_dwordx4 v[72:73], v[62:65], off
	v_mov_b32_e32 v72, v133
	v_mov_b32_e32 v73, v133
	v_cvt_f32_i32_e32 v63, v35
	v_cvt_f32_i32_e32 v62, v34
	v_cvt_f32_i32_e32 v65, v37
	v_cvt_f32_i32_e32 v64, v36
	s_or_b32 s6, s31, 1
	v_pk_mul_f32 v[62:63], v[68:69], v[62:63]
	s_mul_hi_i32 s7, s6, 0x1c000
	v_pk_mul_f32 v[64:65], v[72:73], v[64:65]
	ds_write_b128 v70, v[62:65] offset:16
	s_mul_i32 s6, s6, 0x1c000
	s_add_u32 s6, s71, s6
	s_addc_u32 s7, s72, s7
	v_pk_mul_f32 v[62:63], v[62:63], v[248:249]
	v_lshl_add_u64 v[70:71], s[6:7], 0, v[114:115]
	v_add_co_u32_e32 v70, vcc, 0xe000, v70
	v_pk_mul_f32 v[64:65], v[64:65], v[250:251]
	s_nop 0
	v_addc_co_u32_e32 v71, vcc, 0, v71, vcc
	global_store_dwordx4 v[70:71], v[62:65], off

.LBB0_1401:
	s_andn2_b64 vcc, exec, s[6:7]
	s_cbranch_vccnz .LBB0_1403
	s_lshl_b64 s[6:7], s[42:43], 2
	s_add_u32 s6, s94, s6
	s_addc_u32 s7, s95, s7
	v_lshl_add_u64 v[74:75], v[204:205], 2, s[6:7]
	global_load_dwordx4 v[248:251], v[74:75], off offset:528
	s_add_u32 s6, s71, s56
	s_addc_u32 s7, s72, s35
	s_waitcnt vmcnt(0)
	v_pk_mul_f32 v[62:63], v[62:63], v[248:249]
	v_lshl_add_u64 v[70:71], s[6:7], 0, v[114:115]
	v_add_co_u32_e32 v70, vcc, s1, v70
	v_pk_mul_f32 v[64:65], v[64:65], v[250:251]
	s_nop 0
	v_addc_co_u32_e32 v71, vcc, 0, v71, vcc
	global_store_dwordx4 v[70:71], v[62:65], off offset:16
	v_mov_b32_e32 v70, v133
	v_mov_b32_e32 v71, v133
	v_cvt_f32_i32_e32 v63, v3
	v_cvt_f32_i32_e32 v62, v2
	v_cvt_f32_i32_e32 v65, v5
	v_cvt_f32_i32_e32 v64, v4
	s_or_b32 s6, s31, 1
	v_pk_mul_f32 v[62:63], v[68:69], v[62:63]
	s_mul_hi_i32 s7, s6, 0x1c000
	v_pk_mul_f32 v[64:65], v[70:71], v[64:65]
	ds_write_b128 v66, v[62:65] offset:16
	s_mul_i32 s6, s6, 0x1c000
	s_add_u32 s6, s71, s6
	s_addc_u32 s7, s72, s7
	v_pk_mul_f32 v[62:63], v[62:63], v[248:249]
	v_lshl_add_u64 v[66:67], s[6:7], 0, v[114:115]
	v_add_co_u32_e32 v66, vcc, 0xe000, v66
	v_pk_mul_f32 v[64:65], v[64:65], v[250:251]
	s_nop 0
	v_addc_co_u32_e32 v67, vcc, 0, v67, vcc
	global_store_dwordx4 v[66:67], v[62:65], off offset:16

.LBB0_1422:
	s_lshl_b32 s2, s2, 11
	s_add_i32 m0, s64, s2
	s_lshl_b32 s2, s34, 8
	s_ashr_i32 s3, s2, 31
	v_lshl_add_u64 v[2:3], s[2:3], 2, v[152:153]
	global_load_lds_dword v[2:3], off
	s_and_b64 vcc, exec, s[4:5]
	s_cbranch_vccnz .LBB0_1362
	s_barrier
	s_branch .LBB0_1362
	s_nop 0
	s_nop 0
	s_nop 0
	s_nop 0
	s_nop 0
	s_nop 0
	s_nop 0
	s_nop 0
	s_nop 0
	s_nop 0
	s_nop 0
	s_nop 0
	s_nop 0
	s_nop 0
	s_nop 0
	s_nop 0
	s_nop 0
	s_nop 0
	s_nop 0
	s_nop 0
	s_nop 0
	s_nop 0
	s_nop 0
	s_nop 0

.LBB0_2061:
	s_or_b64 exec, exec, s[2:3]
	s_lshl_b32 s2, s40, 7
	v_lshlrev_b32_e32 v204, 3, v239
	s_or_b32 s2, s2, s62
	v_cvt_f32_i32_e32 v195, v119
	v_cvt_f32_i32_e32 v194, v118
	v_cvt_f32_i32_e32 v193, v121
	v_cvt_f32_i32_e32 v192, v120
	v_cvt_f32_i32_e32 v191, v115
	v_cvt_f32_i32_e32 v190, v114
	v_cvt_f32_i32_e32 v189, v117
	v_cvt_f32_i32_e32 v188, v116
	v_add_u32_e32 v186, s2, v204
	s_lshl_b32 s40, s40, 8
	s_lshl_b32 s31, s38, 1
	v_ashrrev_i32_e32 v187, 31, v186
	v_or_b32_e32 v122, s39, v222
	s_ashr_i32 s41, s40, 31
	v_ashrrev_i32_e32 v205, 31, v204
	v_cmp_eq_u32_e64 s[2:3], 0, v122
	s_mul_hi_i32 s42, s31, 0x1c000
	s_mul_i32 s43, s31, 0x1c000
	v_lshlrev_b64 v[114:115], 2, v[186:187]
	s_and_saveexec_b64 s[18:19], s[2:3]
	s_cbranch_execz .LBB0_2063
	s_lshl_b64 s[90:91], s[40:41], 2
	s_add_u32 s90, s79, s90
	s_addc_u32 s91, s80, s91
	v_lshl_add_u64 v[124:125], v[204:205], 2, s[90:91]
	global_load_dwordx4 v[244:247], v[124:125], off
	s_add_u32 s90, s55, s43
	v_pk_mul_f32 v[120:121], v[162:163], v[192:193] op_sel_hi:[0,1]
	v_pk_mul_f32 v[122:123], v[162:163], v[194:195] op_sel_hi:[0,1]
	s_addc_u32 s91, s56, s42
	s_or_b32 s87, s31, 1
	s_waitcnt vmcnt(0)
	v_pk_mul_f32 v[116:117], v[122:123], v[244:245]
	v_pk_mul_f32 v[118:119], v[120:121], v[246:247]
	v_lshl_add_u64 v[120:121], s[90:91], 0, v[114:115]
	global_store_dwordx4 v[120:121], v[116:119], off
	s_mul_hi_i32 s91, s87, 0x1c000
	s_mul_i32 s87, s87, 0x1c000
	s_add_u32 s90, s55, s87
	v_pk_mul_f32 v[120:121], v[162:163], v[188:189] op_sel:[1,0]
	v_pk_mul_f32 v[122:123], v[162:163], v[190:191] op_sel:[1,0]
	s_addc_u32 s91, s56, s91
	v_pk_mul_f32 v[116:117], v[122:123], v[244:245]
	v_pk_mul_f32 v[118:119], v[120:121], v[246:247]
	v_lshl_add_u64 v[120:121], s[90:91], 0, v[114:115]
	global_store_dwordx4 v[120:121], v[116:119], off

.LBB0_2065:
	s_or_b64 exec, exec, s[18:19]
	v_cvt_f32_i32_e32 v121, v103
	v_cvt_f32_i32_e32 v120, v102
	v_cvt_f32_i32_e32 v125, v105
	v_cvt_f32_i32_e32 v124, v104
	v_cvt_f32_i32_e32 v119, v99
	v_cvt_f32_i32_e32 v118, v98
	v_cvt_f32_i32_e32 v123, v101
	v_cvt_f32_i32_e32 v122, v100
	s_and_saveexec_b64 s[18:19], s[2:3]
	s_cbranch_execz .LBB0_2067
	s_lshl_b64 s[90:91], s[40:41], 2
	s_add_u32 s90, s79, s90
	s_addc_u32 s91, s80, s91
	v_lshl_add_u64 v[108:109], v[204:205], 2, s[90:91]
	global_load_dwordx4 v[244:247], v[108:109], off offset:16
	s_add_u32 s90, s55, s43
	v_pk_mul_f32 v[102:103], v[162:163], v[124:125] op_sel_hi:[0,1]
	v_pk_mul_f32 v[104:105], v[162:163], v[120:121] op_sel_hi:[0,1]
	s_addc_u32 s91, s56, s42
	s_or_b32 s87, s31, 1
	s_waitcnt vmcnt(0)
	v_pk_mul_f32 v[98:99], v[104:105], v[244:245]
	v_pk_mul_f32 v[100:101], v[102:103], v[246:247]
	v_lshl_add_u64 v[102:103], s[90:91], 0, v[114:115]
	global_store_dwordx4 v[102:103], v[98:101], off offset:16
	s_mul_hi_i32 s91, s87, 0x1c000
	s_mul_i32 s87, s87, 0x1c000
	s_add_u32 s90, s55, s87
	v_pk_mul_f32 v[102:103], v[162:163], v[122:123] op_sel:[1,0]
	v_pk_mul_f32 v[104:105], v[162:163], v[118:119] op_sel:[1,0]
	s_addc_u32 s91, s56, s91
	v_pk_mul_f32 v[98:99], v[104:105], v[244:245]
	v_pk_mul_f32 v[100:101], v[102:103], v[246:247]
	v_lshl_add_u64 v[102:103], s[90:91], 0, v[114:115]
	global_store_dwordx4 v[102:103], v[98:101], off offset:16

.LBB0_2069:
	s_or_b64 exec, exec, s[18:19]
	v_cvt_f32_i32_e32 v221, v87
	v_cvt_f32_i32_e32 v220, v86
	v_cvt_f32_i32_e32 v219, v89
	v_cvt_f32_i32_e32 v218, v88
	v_cvt_f32_i32_e32 v217, v83
	v_cvt_f32_i32_e32 v216, v82
	v_cvt_f32_i32_e32 v215, v85
	v_cvt_f32_i32_e32 v214, v84
	s_and_saveexec_b64 s[18:19], s[2:3]
	s_cbranch_execz .LBB0_2071
	s_lshl_b64 s[90:91], s[40:41], 2
	s_add_u32 s90, s79, s90
	s_addc_u32 s91, s80, s91
	v_lshl_add_u64 v[90:91], v[204:205], 2, s[90:91]
	global_load_dwordx4 v[244:247], v[90:91], off offset:512
	s_add_u32 s90, s55, s43
	v_pk_mul_f32 v[86:87], v[162:163], v[218:219] op_sel_hi:[0,1]
	s_addc_u32 s91, s56, s42
	v_pk_mul_f32 v[88:89], v[162:163], v[220:221] op_sel_hi:[0,1]
	s_or_b32 s87, s31, 1
	s_waitcnt vmcnt(0)
	v_pk_mul_f32 v[84:85], v[86:87], v[246:247]
	v_lshl_add_u64 v[86:87], s[90:91], 0, v[114:115]
	v_add_co_u32_e32 v86, vcc, s17, v86
	v_pk_mul_f32 v[82:83], v[88:89], v[244:245]
	s_nop 0
	v_addc_co_u32_e32 v87, vcc, 0, v87, vcc
	global_store_dwordx4 v[86:87], v[82:85], off
	s_mul_hi_i32 s91, s87, 0x1c000
	s_mul_i32 s87, s87, 0x1c000
	s_add_u32 s90, s55, s87
	v_pk_mul_f32 v[86:87], v[162:163], v[214:215] op_sel:[1,0]
	s_addc_u32 s91, s56, s91
	v_pk_mul_f32 v[88:89], v[162:163], v[216:217] op_sel:[1,0]
	v_pk_mul_f32 v[84:85], v[86:87], v[246:247]
	v_lshl_add_u64 v[86:87], s[90:91], 0, v[114:115]
	v_add_co_u32_e32 v86, vcc, 0xe000, v86
	v_pk_mul_f32 v[82:83], v[88:89], v[244:245]
	s_nop 0
	v_addc_co_u32_e32 v87, vcc, 0, v87, vcc
	global_store_dwordx4 v[86:87], v[82:85], off

.LBB0_2073:
	s_or_b64 exec, exec, s[18:19]
	v_cvt_f32_i32_e32 v181, v71
	v_cvt_f32_i32_e32 v180, v70
	v_cvt_f32_i32_e32 v185, v73
	v_cvt_f32_i32_e32 v184, v72
	v_cvt_f32_i32_e32 v179, v67
	v_cvt_f32_i32_e32 v178, v66
	v_cvt_f32_i32_e32 v183, v69
	v_cvt_f32_i32_e32 v182, v68
	s_and_saveexec_b64 s[18:19], s[2:3]
	s_cbranch_execz .LBB0_2075
	s_lshl_b64 s[2:3], s[40:41], 2
	s_add_u32 s2, s79, s2
	s_addc_u32 s3, s80, s3
	v_lshl_add_u64 v[74:75], v[204:205], 2, s[2:3]
	global_load_dwordx4 v[244:247], v[74:75], off offset:528
	s_add_u32 s2, s55, s43
	v_pk_mul_f32 v[70:71], v[162:163], v[184:185] op_sel_hi:[0,1]
	s_addc_u32 s3, s56, s42
	v_pk_mul_f32 v[72:73], v[162:163], v[180:181] op_sel_hi:[0,1]
	s_waitcnt vmcnt(0)
	v_pk_mul_f32 v[68:69], v[70:71], v[246:247]
	v_lshl_add_u64 v[70:71], s[2:3], 0, v[114:115]
	v_add_co_u32_e32 v70, vcc, s17, v70
	v_pk_mul_f32 v[66:67], v[72:73], v[244:245]
	s_nop 0
	v_addc_co_u32_e32 v71, vcc, 0, v71, vcc
	global_store_dwordx4 v[70:71], v[66:69], off offset:16
	s_or_b32 s2, s31, 1
	s_mul_hi_i32 s3, s2, 0x1c000
	s_mul_i32 s2, s2, 0x1c000
	s_add_u32 s2, s55, s2
	v_pk_mul_f32 v[70:71], v[162:163], v[182:183] op_sel:[1,0]
	s_addc_u32 s3, s56, s3
	v_pk_mul_f32 v[72:73], v[162:163], v[178:179] op_sel:[1,0]
	v_pk_mul_f32 v[68:69], v[70:71], v[246:247]
	v_lshl_add_u64 v[70:71], s[2:3], 0, v[114:115]
	v_add_co_u32_e32 v70, vcc, 0xe000, v70
	v_pk_mul_f32 v[66:67], v[72:73], v[244:245]
	s_nop 0
	v_addc_co_u32_e32 v71, vcc, 0, v71, vcc
	global_store_dwordx4 v[70:71], v[66:69], off offset:16
.LBB0_2075:
	s_or_b64 exec, exec, s[18:19]
	s_waitcnt lgkmcnt(0)
	v_fmamk_f32 v66, v130, 0x39800000, v237
	v_rsq_f32_e32 v66, v66
	v_fmamk_f32 v67, v131, 0x39800000, v237
	v_rsq_f32_e32 v67, v67
	v_fmamk_f32 v68, v132, 0x39800000, v237
	v_pk_mul_f32 v[130:131], v[134:135], v[66:67]
	v_cvt_f32_i32_e32 v135, v63
	v_cvt_f32_i32_e32 v134, v62
	v_cndmask_b32_e64 v66, 0, 1, s[10:11]
	v_rsq_f32_e32 v68, v68
	v_fmamk_f32 v69, v133, 0x39800000, v237
	v_cmp_ne_u32_e64 s[2:3], 1, v66
	v_rsq_f32_e32 v69, v69
	s_nop 0
	v_pk_mul_f32 v[132:133], v[136:137], v[68:69]
	v_cvt_f32_i32_e32 v137, v65
	v_cvt_f32_i32_e32 v136, v64
	s_and_saveexec_b64 s[18:19], s[4:5]
	s_cbranch_execz .LBB0_2092
	v_add_lshl_u32 v66, s68, v106, 4
	v_add_u32_e32 v68, 0, v66
	v_mov_b32_e32 v67, v132
	v_pk_mul_f32 v[64:65], v[132:133], v[136:137] op_sel_hi:[0,1]
	v_pk_mul_f32 v[62:63], v[132:133], v[134:135] op_sel_hi:[0,1]
	v_add_u32_e32 v68, 0x20c00, v68
	s_and_b64 vcc, exec, s[2:3]
	ds_write_b128 v68, v[62:65]
	s_cbranch_vccnz .LBB0_2078
	s_lshl_b64 s[4:5], s[40:41], 2
	s_add_u32 s4, s79, s4
	s_addc_u32 s5, s80, s5
	v_lshl_add_u64 v[68:69], v[204:205], 2, s[4:5]
	global_load_dwordx4 v[248:251], v[68:69], off
	s_add_u32 s4, s57, s43
	s_addc_u32 s5, s60, s42
	s_waitcnt vmcnt(0)
	v_pk_mul_f32 v[64:65], v[64:65], v[250:251]
	v_pk_mul_f32 v[62:63], v[62:63], v[248:249]
	v_lshl_add_u64 v[68:69], v[186:187], 2, s[4:5]
	global_store_dwordx4 v[68:69], v[62:65], off
.LBB0_2078:
	s_nop 1
	v_cvt_f32_i32_e32 v63, v59
	v_cvt_f32_i32_e32 v65, v61
	v_cvt_f32_i32_e32 v64, v60
	v_cvt_f32_i32_e32 v62, v58
	v_mov_b32_e32 v68, v133
	v_add_u32_e32 v66, s77, v66
	v_pk_mul_f32 v[64:65], v[68:69], v[64:65] op_sel_hi:[0,1]
	v_pk_mul_f32 v[62:63], v[68:69], v[62:63] op_sel_hi:[0,1]
	s_and_b64 vcc, exec, s[2:3]
	ds_write_b128 v66, v[62:65] offset:16
	s_cbranch_vccnz .LBB0_2080
	s_lshl_b64 s[4:5], s[40:41], 2
	s_add_u32 s4, s79, s4
	s_addc_u32 s5, s80, s5
	v_lshl_add_u64 v[68:69], v[204:205], 2, s[4:5]
	s_or_b32 s4, s31, 1
	s_mul_hi_i32 s5, s4, 0x1c000
	s_mul_i32 s4, s4, 0x1c000
	s_add_u32 s4, s57, s4
	s_addc_u32 s5, s60, s5
	v_pk_mul_f32 v[64:65], v[64:65], v[250:251]
	v_pk_mul_f32 v[62:63], v[62:63], v[248:249]
	v_lshl_add_u64 v[68:69], v[186:187], 2, s[4:5]
	global_store_dwordx4 v[68:69], v[62:65], off

.LBB0_2082:
	s_andn2_b64 vcc, exec, s[4:5]
	s_cbranch_vccnz .LBB0_2084
	s_lshl_b64 s[4:5], s[40:41], 2
	s_add_u32 s4, s79, s4
	s_addc_u32 s5, s80, s5
	v_lshl_add_u64 v[76:77], v[204:205], 2, s[4:5]
	global_load_dwordx4 v[248:251], v[76:77], off offset:16
	s_add_u32 s4, s57, s43
	s_addc_u32 s5, s60, s42
	s_waitcnt vmcnt(0)
	v_pk_mul_f32 v[64:65], v[64:65], v[250:251]
	v_pk_mul_f32 v[62:63], v[62:63], v[248:249]
	v_lshl_add_u64 v[72:73], s[4:5], 0, v[114:115]
	global_store_dwordx4 v[72:73], v[62:65], off offset:16
	v_mov_b32_e32 v72, v133
	v_mov_b32_e32 v73, v133
	v_cvt_f32_i32_e32 v63, v27
	v_cvt_f32_i32_e32 v62, v26
	v_cvt_f32_i32_e32 v65, v29
	v_cvt_f32_i32_e32 v64, v28
	s_or_b32 s4, s31, 1
	v_pk_mul_f32 v[62:63], v[68:69], v[62:63]
	s_mul_hi_i32 s5, s4, 0x1c000
	v_pk_mul_f32 v[64:65], v[72:73], v[64:65]
	ds_write_b128 v70, v[62:65] offset:16
	s_mul_i32 s4, s4, 0x1c000
	s_add_u32 s4, s57, s4
	s_addc_u32 s5, s60, s5
	v_pk_mul_f32 v[64:65], v[64:65], v[250:251]
	v_pk_mul_f32 v[62:63], v[62:63], v[248:249]
	v_lshl_add_u64 v[70:71], s[4:5], 0, v[114:115]
	global_store_dwordx4 v[70:71], v[62:65], off offset:16

.LBB0_2086:
	s_andn2_b64 vcc, exec, s[4:5]
	s_cbranch_vccnz .LBB0_2088
	s_lshl_b64 s[4:5], s[40:41], 2
	s_add_u32 s4, s79, s4
	s_addc_u32 s5, s80, s5
	v_lshl_add_u64 v[76:77], v[204:205], 2, s[4:5]
	global_load_dwordx4 v[248:251], v[76:77], off offset:512
	s_add_u32 s4, s57, s43
	s_addc_u32 s5, s60, s42
	s_waitcnt vmcnt(0)
	v_pk_mul_f32 v[62:63], v[62:63], v[248:249]
	v_lshl_add_u64 v[72:73], s[4:5], 0, v[114:115]
	v_add_co_u32_e32 v72, vcc, s17, v72
	v_pk_mul_f32 v[64:65], v[64:65], v[250:251]
	s_nop 0
	v_addc_co_u32_e32 v73, vcc, 0, v73, vcc
	global_store_dwordx4 v[72:73], v[62:65], off
	v_mov_b32_e32 v72, v133
	v_mov_b32_e32 v73, v133
	v_cvt_f32_i32_e32 v63, v35
	v_cvt_f32_i32_e32 v62, v34
	v_cvt_f32_i32_e32 v65, v37
	v_cvt_f32_i32_e32 v64, v36
	s_or_b32 s4, s31, 1
	v_pk_mul_f32 v[62:63], v[68:69], v[62:63]
	s_mul_hi_i32 s5, s4, 0x1c000
	v_pk_mul_f32 v[64:65], v[72:73], v[64:65]
	ds_write_b128 v70, v[62:65] offset:16
	s_mul_i32 s4, s4, 0x1c000
	s_add_u32 s4, s57, s4
	s_addc_u32 s5, s60, s5
	v_pk_mul_f32 v[62:63], v[62:63], v[248:249]
	v_lshl_add_u64 v[70:71], s[4:5], 0, v[114:115]
	v_add_co_u32_e32 v70, vcc, 0xe000, v70
	v_pk_mul_f32 v[64:65], v[64:65], v[250:251]
	s_nop 0
	v_addc_co_u32_e32 v71, vcc, 0, v71, vcc
	global_store_dwordx4 v[70:71], v[62:65], off

.LBB0_2090:
	s_andn2_b64 vcc, exec, s[4:5]
	s_cbranch_vccnz .LBB0_2092
	s_lshl_b64 s[4:5], s[40:41], 2
	s_add_u32 s4, s79, s4
	s_addc_u32 s5, s80, s5
	v_lshl_add_u64 v[74:75], v[204:205], 2, s[4:5]
	global_load_dwordx4 v[248:251], v[74:75], off offset:528
	s_add_u32 s4, s57, s43
	s_addc_u32 s5, s60, s42
	s_waitcnt vmcnt(0)
	v_pk_mul_f32 v[62:63], v[62:63], v[248:249]
	v_lshl_add_u64 v[70:71], s[4:5], 0, v[114:115]
	v_add_co_u32_e32 v70, vcc, s17, v70
	v_pk_mul_f32 v[64:65], v[64:65], v[250:251]
	s_nop 0
	v_addc_co_u32_e32 v71, vcc, 0, v71, vcc
	global_store_dwordx4 v[70:71], v[62:65], off offset:16
	v_mov_b32_e32 v70, v133
	v_mov_b32_e32 v71, v133
	v_cvt_f32_i32_e32 v63, v3
	v_cvt_f32_i32_e32 v62, v2
	v_cvt_f32_i32_e32 v65, v5
	v_cvt_f32_i32_e32 v64, v4
	s_or_b32 s4, s31, 1
	v_pk_mul_f32 v[62:63], v[68:69], v[62:63]
	s_mul_hi_i32 s5, s4, 0x1c000
	v_pk_mul_f32 v[64:65], v[70:71], v[64:65]
	ds_write_b128 v66, v[62:65] offset:16
	s_mul_i32 s4, s4, 0x1c000
	s_add_u32 s4, s57, s4
	s_addc_u32 s5, s60, s5
	v_pk_mul_f32 v[62:63], v[62:63], v[248:249]
	v_lshl_add_u64 v[66:67], s[4:5], 0, v[114:115]
	v_add_co_u32_e32 v66, vcc, 0xe000, v66
	v_pk_mul_f32 v[64:65], v[64:65], v[250:251]
	s_nop 0
	v_addc_co_u32_e32 v67, vcc, 0, v67, vcc
	global_store_dwordx4 v[66:67], v[62:65], off offset:16

.LBB0_2111:
	s_lshl_b32 s0, s0, 11
	s_add_i32 m0, s48, s0
	s_lshl_b32 s0, s30, 8
	s_ashr_i32 s1, s0, 31
	v_lshl_add_u64 v[2:3], s[0:1], 2, v[152:153]
	global_load_lds_dword v[2:3], off
	s_and_b64 vcc, exec, s[2:3]
	s_cbranch_vccnz .LBB0_2051
	s_barrier
	s_branch .LBB0_2051
	s_nop 0
	s_nop 0
	s_nop 0
	s_nop 0
	s_nop 0
	s_nop 0
	s_nop 0
	s_nop 0
	s_nop 0
	s_nop 0
	s_nop 0
	s_nop 0
	s_nop 0
	s_nop 0
	s_nop 0
	s_nop 0
	s_nop 0
	s_nop 0
	s_nop 0
	s_nop 0
	s_nop 0
	s_nop 0
	s_nop 0
	s_nop 0
